# sgemm2 (sample residual GEMM tail) K loop: LDS fragment reads issued right after the barrier, the slab+2 LDS-DMA loads issued behind them from pre-computed addresses
# baseline (speedup 1.0000x reference)
.LBB0_969:
	s_add_i32 s49, s24, 0x10000
	s_and_b32 s49, s49, 0x18000
	s_add_i32 s49, s57, s49
	s_and_b32 vcc_lo, s24, 0x18000
	s_add_i32 vcc_lo, s33, vcc_lo
	v_add_u32_e32 v2, vcc_lo, v30
	v_add_u32_e32 v33, s84, v2
	v_lshl_add_u64 v[78:79], s[8:9], 0, v[22:23]
	v_lshl_add_u64 v[80:81], s[10:11], 0, v[22:23]
	v_lshl_add_u64 v[82:83], s[16:17], 0, v[22:23]
	v_lshl_add_u64 v[84:85], s[18:19], 0, v[22:23]
	s_add_i32 s52, s49, 0x2000
	s_add_i32 s51, s49, 0x4000
	s_add_i32 s50, s49, 0x6000
	s_waitcnt vmcnt(4)
	s_barrier
	ds_read_b128 v[34:37], v33
	ds_read_b128 v[38:41], v2 offset:8192
	ds_read_b128 v[50:53], v2 offset:10240
	ds_read_b128 v[54:57], v2 offset:12288
	ds_read_b128 v[58:61], v2 offset:14336
	ds_read_b128 v[46:49], v33 offset:1024
	ds_read_b128 v[62:65], v2 offset:9216
	ds_read_b128 v[66:69], v2 offset:11264
	ds_read_b128 v[70:73], v2 offset:13312
	ds_read_b128 v[74:77], v2 offset:15360
	s_mov_b32 m0, s49
	s_add_i32 s48, s48, 1
	global_load_lds_dwordx4 v[78:79], off
	s_mov_b32 m0, s52
	s_add_i32 s24, s24, 0x8000
	global_load_lds_dwordx4 v[80:81], off
	s_mov_b32 m0, s51
	s_add_u32 s8, s8, 0x80
	global_load_lds_dwordx4 v[82:83], off
	s_mov_b32 m0, s50
	s_addc_u32 s9, s9, 0
	global_load_lds_dwordx4 v[84:85], off
	s_add_u32 s10, s10, 0x80
	s_addc_u32 s11, s11, 0
	s_add_u32 s16, s16, 0x80
	s_addc_u32 s17, s17, 0
	s_add_u32 s18, s18, 0x80
	s_addc_u32 s19, s19, 0
	s_waitcnt lgkmcnt(8)
	v_mfma_f32_16x16x32_bf16 v[4:7], v[38:41], v[34:37], v[4:7]
	s_waitcnt lgkmcnt(7)
	v_mfma_f32_16x16x32_bf16 v[8:11], v[50:53], v[34:37], v[8:11]
	s_waitcnt lgkmcnt(6)
	v_mfma_f32_16x16x32_bf16 v[12:15], v[54:57], v[34:37], v[12:15]
	s_waitcnt lgkmcnt(5)
	v_mfma_f32_16x16x32_bf16 v[16:19], v[58:61], v[34:37], v[16:19]
	s_waitcnt lgkmcnt(3)
	v_mfma_f32_16x16x32_bf16 v[4:7], v[62:65], v[46:49], v[4:7]
	s_waitcnt lgkmcnt(2)
	v_mfma_f32_16x16x32_bf16 v[8:11], v[66:69], v[46:49], v[8:11]
	s_waitcnt lgkmcnt(1)
	v_mfma_f32_16x16x32_bf16 v[12:15], v[70:73], v[46:49], v[12:15]
	s_cmp_eq_u32 s27, s48
	s_waitcnt lgkmcnt(0)
	v_mfma_f32_16x16x32_bf16 v[16:19], v[74:77], v[46:49], v[16:19]
	s_cbranch_scc0 .LBB0_969
	s_lshl_b32 s8, s27, 15
	s_and_b32 s8, s8, 0x18000
	s_add_i32 s8, s33, s8
	v_add_u32_e32 v2, s8, v30
	s_waitcnt vmcnt(4)
	s_barrier
	v_add_u32_e32 v33, s84, v2
	ds_read_b128 v[34:37], v33
	ds_read_b128 v[38:41], v2 offset:8192
	ds_read_b128 v[50:53], v2 offset:10240
	ds_read_b128 v[54:57], v2 offset:12288
	ds_read_b128 v[58:61], v2 offset:14336
	ds_read_b128 v[46:49], v33 offset:1024
	ds_read_b128 v[62:65], v2 offset:9216
	ds_read_b128 v[66:69], v2 offset:11264
	ds_read_b128 v[70:73], v2 offset:13312
	ds_read_b128 v[74:77], v2 offset:15360
	v_readlane_b32 s8, v254, 13
	v_readlane_b32 s9, v254, 14
	s_waitcnt lgkmcnt(8)
	v_mfma_f32_16x16x32_bf16 v[4:7], v[38:41], v[34:37], v[4:7]
	s_waitcnt lgkmcnt(7)
	v_mfma_f32_16x16x32_bf16 v[8:11], v[50:53], v[34:37], v[8:11]
	s_waitcnt lgkmcnt(6)
	v_mfma_f32_16x16x32_bf16 v[12:15], v[54:57], v[34:37], v[12:15]
	s_waitcnt lgkmcnt(5)
	v_mfma_f32_16x16x32_bf16 v[16:19], v[58:61], v[34:37], v[16:19]
	s_waitcnt lgkmcnt(3)
	v_mfma_f32_16x16x32_bf16 v[4:7], v[62:65], v[46:49], v[4:7]
	s_waitcnt lgkmcnt(2)
	v_mfma_f32_16x16x32_bf16 v[8:11], v[66:69], v[46:49], v[8:11]
	s_waitcnt lgkmcnt(1)
	v_mfma_f32_16x16x32_bf16 v[12:15], v[70:73], v[46:49], v[12:15]
	s_waitcnt lgkmcnt(0)
	v_mfma_f32_16x16x32_bf16 v[16:19], v[74:77], v[46:49], v[16:19]
	s_and_b64 vcc, exec, s[8:9]
	s_waitcnt vmcnt(0)
	s_barrier
	v_add_u32_e32 v2, s33, v31
	ds_read_b128 v[34:37], v32
	ds_read_b128 v[38:41], v2 offset:8192
	ds_read_b128 v[50:53], v2 offset:10240
	ds_read_b128 v[54:57], v2 offset:12288
	ds_read_b128 v[58:61], v2 offset:14336
	ds_read_b128 v[46:49], v32 offset:1024
	ds_read_b128 v[62:65], v2 offset:9216
	ds_read_b128 v[66:69], v2 offset:11264
	ds_read_b128 v[70:73], v2 offset:13312
	ds_read_b128 v[74:77], v2 offset:15360
	s_waitcnt lgkmcnt(8)
	v_mfma_f32_16x16x32_bf16 v[4:7], v[38:41], v[34:37], v[4:7]
	s_waitcnt lgkmcnt(7)
	v_mfma_f32_16x16x32_bf16 v[8:11], v[50:53], v[34:37], v[8:11]
	s_waitcnt lgkmcnt(6)
	v_mfma_f32_16x16x32_bf16 v[12:15], v[54:57], v[34:37], v[12:15]
	s_waitcnt lgkmcnt(5)
	v_mfma_f32_16x16x32_bf16 v[16:19], v[58:61], v[34:37], v[16:19]
	s_waitcnt lgkmcnt(3)
	v_mfma_f32_16x16x32_bf16 v[4:7], v[62:65], v[46:49], v[4:7]
	s_waitcnt lgkmcnt(2)
	v_mfma_f32_16x16x32_bf16 v[8:11], v[66:69], v[46:49], v[8:11]
	s_waitcnt lgkmcnt(1)
	v_mfma_f32_16x16x32_bf16 v[12:15], v[70:73], v[46:49], v[12:15]
	s_waitcnt lgkmcnt(0)
	v_mfma_f32_16x16x32_bf16 v[16:19], v[74:77], v[46:49], v[16:19]
	s_nop 1
	s_barrier
	s_cbranch_vccz .LBB0_974
	v_add_u32_e32 v2, s85, v24
	ds_write_b128 v2, v[4:7]
	ds_write_b128 v2, v[8:11] offset:1024
	ds_write_b128 v2, v[12:15] offset:2048
	s_nop 2
	ds_write_b128 v2, v[16:19] offset:3072
	s_and_saveexec_b64 s[8:9], s[4:5]
	ds_write_b32 v28, v3 offset:16384
	s_or_b64 exec, exec, s[8:9]
